# v49 + the 44 workgroups with 14 in-proj tiles start the phase ~16 us late (run 1)
# speedup vs baseline: 1.0047x; 1.0047x over previous
; #define GAS __attribute__((address_space(1)))
;     __device__ __forceinline__ GAS float* outp() const { return (GAS float*)rd(17); }
;     __device__ __forceinline__ GAS unsigned char* wsp() const { return (GAS unsigned char*)rd(18); }
; #define F_qng F.in(9)
; __global__ void __launch_bounds__(512, 2) mega_fwd(Params p) {
;     ...
;         if (IN(pb + 1)) { pg8::Gemm g{(const GAS bf16*)(F.wsp() + WS_XN), (const GAS bf16*)(F.wsp() + WS_WIN) + (size_t)l * NPROJ * D, 0, 0, MTOT / 256, NPROJ / 256, 1, D, 0, WGM_PROJ};
;             pg8::Order S; S.init(g, F.G, (int)blockIdx.x);
;             pg8::EpiProj E{l, F.wsp(), F.outp(), F_qng + l * 128, F_kng + l * 128, (const GAS float*)(F.wsp() + WS_LB) + l * 1024};
;             pg8::gemm_phase(F.lds, g, S, E, F.wave);
.LBB0_172:
	s_cmpk_lt_u32 s101, 0xd4
	s_cbranch_scc1 .Lip_nodelay
	s_movk_i32 s100, 4
.Lip_dl:
	s_sleep 127
	s_sub_u32 s100, s100, 1
	s_cmp_lg_u32 s100, 0
	s_cbranch_scc1 .Lip_dl
